# prefetch input x (one dword per 128B line) at kernel start so LN_0 and the layer-0 residual epilogue read it from the Infinity Cache
# speedup vs baseline: 1.0012x; 1.0012x over previous
; __global__ void __launch_bounds__(NT, 2) fwd_kernel(Params p) {
;   cg::grid_group grid = cg::this_grid();
;   __shared__ __attribute__((aligned(16))) bf16 lds[GEMM_LDS_BF16 + 256];
;   float* sm = (float*)lds;
;   unsigned char* ws = p.ws;
;   Ctx c{p, sm};
;   __shared__ unsigned bar_st[2];
;   if (threadIdx.x == 0) { bar_st[0] = 0u; bar_st[1] = 0u; }
;   __syncthreads();
;   (void)xcd_barrier_post((unsigned*)(ws + WS_BAR), bar_st);
_Z10fwd_kernel6Params:
	s_load_dwordx2 s[88:89], s[0:1], 0xb0
	s_load_dwordx4 s[4:7], s[0:1], 0xa0
	s_mov_b32 s38, s2
	s_add_u32 s2, s0, 0xb8
	s_addc_u32 s3, s1, 0
	v_and_b32_e32 v172, 0x3ff, v0
	s_load_dwordx2 s[12:13], s[0:1], 0x0
	s_lshl_b32 s14, s38, 8
	v_add_lshl_u32 v228, v172, s14, 7
	v_add_u32_e32 v229, 0x1000000, v228
	v_add_u32_e32 v230, 0x2000000, v228
	v_add_u32_e32 v231, 0x3000000, v228
	s_waitcnt lgkmcnt(0)
	global_load_dword v232, v228, s[12:13]
	global_load_dword v233, v229, s[12:13]
	global_load_dword v234, v230, s[12:13]
	global_load_dword v236, v231, s[12:13]
	v_writelane_b32 v255, 1, 1
	v_writelane_b32 v255, 0, 4
	s_waitcnt lgkmcnt(0)
	v_writelane_b32 v252, s4, 0
	s_nop 1
	v_writelane_b32 v252, s5, 1
	v_writelane_b32 v252, s6, 2
	v_writelane_b32 v252, s7, 3
	s_load_dwordx8 s[4:11], s[0:1], 0x80
	s_waitcnt lgkmcnt(0)
	v_writelane_b32 v252, s4, 4
	s_nop 1
	v_writelane_b32 v252, s5, 5
	v_writelane_b32 v252, s6, 6
	v_writelane_b32 v252, s7, 7
	v_writelane_b32 v252, s8, 8
	v_writelane_b32 v252, s9, 9
	v_writelane_b32 v252, s10, 10
	v_writelane_b32 v252, s11, 11
	v_writelane_b32 v252, s2, 12
	v_cmp_eq_u32_e64 s[4:5], 0, v172
	s_nop 0
	v_writelane_b32 v252, s3, 13
	s_mov_b64 s[2:3], exec
	v_writelane_b32 v252, s4, 14
	s_nop 1
	v_writelane_b32 v252, s5, 15
	s_and_b64 s[4:5], s[2:3], s[4:5]
	s_mov_b64 exec, s[4:5]
	v_mov_b32_e32 v2, 0
	v_mov_b32_e32 v3, v2
	v_mov_b32_e32 v1, 0x12200
	ds_write_b64 v1, v[2:3]
	s_or_b64 exec, exec, s[2:3]
	s_load_dwordx2 s[40:41], s[0:1], 0xb8
	s_load_dword s23, s[0:1], 0xc0
	s_waitcnt lgkmcnt(0)
	s_barrier
	s_getreg_b32 s6, hwreg(HW_REG_XCC_ID, 0, 4)
	s_mov_b64 s[2:3], exec
	v_readlane_b32 s4, v252, 14
	v_readlane_b32 s5, v252, 15
	s_and_b64 s[4:5], s[2:3], s[4:5]
	s_mov_b64 exec, s[4:5]
	s_cbranch_execz .LBB0_5
	s_mov_b64 s[4:5], exec
	v_mbcnt_lo_u32_b32 v1, s4, 0
	v_mbcnt_hi_u32_b32 v1, s5, v1
	v_cmp_eq_u32_e32 vcc, 0, v1
	s_and_b64 s[8:9], exec, vcc
	s_mov_b64 exec, s[8:9]
	s_cbranch_execz .LBB0_5
	s_lshl_b32 s6, s6, 8
	s_and_b32 s6, s6, 0xf00
	s_bcnt1_i32_b64 s4, s[4:5]
	v_mov_b32_e32 v1, s6
	v_mov_b32_e32 v2, s4
	global_atomic_add v1, v2, s[88:89] offset:1024
